# P0: rotate wave->row assignment so the 256 extra (decode+pad) rows land on waves without a transpose item; plus earlier fixes
# speedup vs baseline: 1.0020x; 1.0019x over previous
.LBB0_14:
	s_cmp_lg_u32 s33, 0x100
	s_cbranch_scc1 .Lp0_noremap
	s_add_i32 s0, s0, 0x100
	s_and_b32 s0, s0, 0x7ff
